# E26 + down-proj K-loop LDS-DMA loads in scalar-base form (no per-load v_lshl_add_u64)
# speedup vs baseline: 1.0012x; 1.0012x over previous
;     __device__ __forceinline__ int nt(const Unit& u) const { return (u.pn >> 1) < 2 ? 22 : 20; }
; #define PG8_STAGE(bufoff, gbase, voff) do { _Pragma("unroll") for (int _i = 0; _i < 2; ++_i) \
;         __builtin_amdgcn_global_load_lds((const unsigned*)((const char*)(gbase) + (voff)[_i]), (LAS unsigned*)(lds + (bufoff) + ldsw + _i * 8192), 16, 0, 0); } while (0)
; #define PG8_LDA(dst, b, h) do { _Pragma("unroll") for (int m = 0; m < 4; ++m) _Pragma("unroll") for (int k = 0; k < 2; ++k) dst[m][k] = *(const LAS bf16x8*)(pA + PG8_SA(b, h) + m * 2048 + k * 1024); } while (0)
; #define PG8_LDB(dst, b, h) do { _Pragma("unroll") for (int n = 0; n < 2; ++n) _Pragma("unroll") for (int k = 0; k < 2; ++k) dst[n][k] = *(const LAS bf16x8*)(pB + (PG8_SB(b, h) - 4 * HTB) + n * 2048 + k * 1024); } while (0)
; #define PG8_MMA(ai, bj, At, Bt) do { __builtin_amdgcn_s_setprio(1); _Pragma("unroll") for (int m = 0; m < 4; ++m) _Pragma("unroll") for (int n = 0; n < 2; ++n) _Pragma("unroll") for (int k = 0; k < 2; ++k) \
;         acc[ai][bj][m][n] = __builtin_amdgcn_mfma_f32_16x16x32_bf16(Bt[n][k], At[m][k], acc[ai][bj][m][n], 0, 0, 0); __builtin_amdgcn_s_setprio(0); } while (0)
; #define PG8_WAIT_V(n) asm volatile("s_waitcnt vmcnt(" #n ")" ::: "memory")
; #define PG8_BAR __builtin_amdgcn_s_barrier()
; template <class Desc, class Epi, bool ALIGN_EPI>
; __device__ __forceinline__ void gemm_phase(LAS unsigned char* lds, const Desc& D, const Epi& E, int G, int c) {
;     ...
;         for (int t = 0; t < nt; t += 2) {
;             const bool last = (t == nt - 2);
;             if (last && has_next) PG8_AWAIT(nxt);
;             const char* a1 = cA + (size_t)(t + 1) * kstep;
;             const char* a2 = last ? nA : cA + (size_t)(t + 2) * kstep; const char* b2 = last ? nB : cB + (size_t)(t + 2) * kstep;
;             const char* a3 = a2 + kstep; const char* b3 = b2 + kstep;
;             PG8_LDB(B0, 0, 0); PG8_LDB(B1, 0, 1); PG8_SCHED; PG8_LDA(At, 0, 0); PG8_STAGE(PG8_SA(1, 1), a1 + hstepA, voffA);
;             PG8_WAIT_V(8); PG8_WAIT_L(0); PG8_BAR; PG8_MMA(0, 0, At, B0); PG8_MMA(0, 1, At, B1); PG8_BAR; PG8_SCHED;
;             PG8_LDA(At, 0, 1); PG8_STAGE(PG8_SB(0, 0), b2, voffB); PG8_STAGE(PG8_SB(0, 1), b2 + hstepB, voffB); PG8_STAGE(PG8_SA(0, 0), a2, voffA);
;             PG8_WAIT_V(8); PG8_WAIT_L(0); PG8_BAR; PG8_MMA(1, 0, At, B0); PG8_MMA(1, 1, At, B1); PG8_BAR; PG8_SCHED;
.LBB0_1580:
	s_or_b32 s14, s30, 1
	s_add_i32 s30, s30, 2
	s_mov_b32 s31, s15
	s_lshl_b64 s[72:73], s[14:15], 7
	s_lshl_b64 s[74:75], s[30:31], 7
	s_add_u32 s14, s18, s74
	ds_read_b128 v[140:143], v163
	ds_read_b128 v[144:147], v163 offset:1024
	ds_read_b128 v[148:151], v163 offset:2048
	ds_read_b128 v[152:155], v163 offset:3072
	ds_read_b128 v[156:159], v163 offset:16384
	ds_read_b128 v[166:169], v163 offset:17408
	ds_read_b128 v[170:173], v163 offset:18432
	ds_read_b128 v[174:177], v163 offset:19456
	s_addc_u32 s31, s19, s75
	s_and_b64 s[46:47], s[34:35], exec
	s_cselect_b32 s47, s43, s31
	s_cselect_b32 s46, s42, s14
	s_add_u32 s14, s20, s74
	s_addc_u32 s31, s21, s75
	s_and_b64 s[34:35], s[34:35], exec
	s_cselect_b32 s35, s3, s31
	s_cselect_b32 s34, s13, s14
	s_add_u32 s14, s18, s72
	s_addc_u32 s31, s19, s73
	s_add_u32 s72, s14, 0x100000
	s_addc_u32 s73, s31, 0
	s_add_i32 m0, s52, 0xc000
	ds_read_b128 v[178:181], v162
	ds_read_b128 v[182:185], v162 offset:1024
	ds_read_b128 v[186:189], v162 offset:2048
	ds_read_b128 v[190:193], v162 offset:3072
	ds_read_b128 v[194:197], v162 offset:4096
	ds_read_b128 v[198:201], v162 offset:5120
	ds_read_b128 v[202:205], v162 offset:6144
	ds_read_b128 v[206:209], v162 offset:7168
	global_load_lds_dwordx4 v132, s[72:73]
	s_add_i32 m0, s52, 0xe000
	s_nop 0
	global_load_lds_dwordx4 v136, s[72:73]
	s_waitcnt vmcnt(8)
	s_waitcnt lgkmcnt(0)
	s_barrier
	v_mfma_f32_16x16x32_bf16 v[128:131], v[140:143], v[178:181], v[128:131]
	v_mfma_f32_16x16x32_bf16 v[128:131], v[144:147], v[182:185], v[128:131]
	v_mfma_f32_16x16x32_bf16 v[124:127], v[148:151], v[178:181], v[124:127]
	v_mfma_f32_16x16x32_bf16 v[124:127], v[152:155], v[182:185], v[124:127]
	v_mfma_f32_16x16x32_bf16 v[96:99], v[156:159], v[178:181], v[96:99]
	v_mfma_f32_16x16x32_bf16 v[96:99], v[166:169], v[182:185], v[96:99]
	v_mfma_f32_16x16x32_bf16 v[92:95], v[170:173], v[178:181], v[92:95]
	v_mfma_f32_16x16x32_bf16 v[92:95], v[174:177], v[182:185], v[92:95]
	v_mfma_f32_16x16x32_bf16 v[84:87], v[170:173], v[186:189], v[84:87]
	v_mfma_f32_16x16x32_bf16 v[84:87], v[174:177], v[190:193], v[84:87]
	v_mfma_f32_16x16x32_bf16 v[88:91], v[156:159], v[186:189], v[88:91]
	v_mfma_f32_16x16x32_bf16 v[88:91], v[166:169], v[190:193], v[88:91]
	v_mfma_f32_16x16x32_bf16 v[116:119], v[148:151], v[186:189], v[116:119]
	v_mfma_f32_16x16x32_bf16 v[116:119], v[152:155], v[190:193], v[116:119]
	v_mfma_f32_16x16x32_bf16 v[120:123], v[140:143], v[186:189], v[120:123]
	v_mfma_f32_16x16x32_bf16 v[120:123], v[144:147], v[190:193], v[120:123]
	v_mfma_f32_16x16x32_bf16 v[112:115], v[140:143], v[194:197], v[112:115]
	v_mfma_f32_16x16x32_bf16 v[112:115], v[144:147], v[198:201], v[112:115]
	v_mfma_f32_16x16x32_bf16 v[108:111], v[148:151], v[194:197], v[108:111]
	v_mfma_f32_16x16x32_bf16 v[108:111], v[152:155], v[198:201], v[108:111]
	v_mfma_f32_16x16x32_bf16 v[80:83], v[156:159], v[194:197], v[80:83]
	v_mfma_f32_16x16x32_bf16 v[80:83], v[166:169], v[198:201], v[80:83]
	v_mfma_f32_16x16x32_bf16 v[76:79], v[170:173], v[194:197], v[76:79]
	v_mfma_f32_16x16x32_bf16 v[76:79], v[174:177], v[198:201], v[76:79]
	v_mfma_f32_16x16x32_bf16 v[68:71], v[170:173], v[202:205], v[68:71]
	v_mfma_f32_16x16x32_bf16 v[68:71], v[174:177], v[206:209], v[68:71]
	v_mfma_f32_16x16x32_bf16 v[72:75], v[156:159], v[202:205], v[72:75]
	v_mfma_f32_16x16x32_bf16 v[72:75], v[166:169], v[206:209], v[72:75]
	v_mfma_f32_16x16x32_bf16 v[100:103], v[148:151], v[202:205], v[100:103]
	v_mfma_f32_16x16x32_bf16 v[100:103], v[152:155], v[206:209], v[100:103]
	v_mfma_f32_16x16x32_bf16 v[104:107], v[140:143], v[202:205], v[104:107]
	v_mfma_f32_16x16x32_bf16 v[104:107], v[144:147], v[206:209], v[104:107]
	s_barrier
	s_mov_b32 m0, s53
	s_add_u32 s72, s34, 0x100000
	s_addc_u32 s73, s35, 0
	ds_read_b128 v[178:181], v162 offset:16384
	ds_read_b128 v[182:185], v162 offset:17408
	ds_read_b128 v[186:189], v162 offset:18432
	ds_read_b128 v[190:193], v162 offset:19456
	ds_read_b128 v[194:197], v162 offset:20480
	ds_read_b128 v[198:201], v162 offset:21504
	ds_read_b128 v[202:205], v162 offset:22528
	ds_read_b128 v[206:209], v162 offset:23552
	global_load_lds_dwordx4 v134, s[34:35]
	s_mov_b32 m0, s54
	s_nop 0
	global_load_lds_dwordx4 v138, s[34:35]
	s_mov_b32 m0, s55
	s_nop 0
	global_load_lds_dwordx4 v134, s[72:73]
	s_mov_b32 m0, s56
	s_nop 0
	global_load_lds_dwordx4 v138, s[72:73]
	s_mov_b32 m0, s52
	s_nop 0
	global_load_lds_dwordx4 v132, s[46:47]
	s_mov_b32 m0, s57
	s_nop 0
	global_load_lds_dwordx4 v136, s[46:47]
	s_waitcnt vmcnt(8)
	s_waitcnt lgkmcnt(0)
	s_barrier
; #define PG8_STAGE(bufoff, gbase, voff) do { _Pragma("unroll") for (int _i = 0; _i < 2; ++_i) \
;         __builtin_amdgcn_global_load_lds((const unsigned*)((const char*)(gbase) + (voff)[_i]), (LAS unsigned*)(lds + (bufoff) + ldsw + _i * 8192), 16, 0, 0); } while (0)
; #define PG8_LDA(dst, b, h) do { _Pragma("unroll") for (int m = 0; m < 4; ++m) _Pragma("unroll") for (int k = 0; k < 2; ++k) dst[m][k] = *(const LAS bf16x8*)(pA + PG8_SA(b, h) + m * 2048 + k * 1024); } while (0)
; #define PG8_LDB(dst, b, h) do { _Pragma("unroll") for (int n = 0; n < 2; ++n) _Pragma("unroll") for (int k = 0; k < 2; ++k) dst[n][k] = *(const LAS bf16x8*)(pB + (PG8_SB(b, h) - 4 * HTB) + n * 2048 + k * 1024); } while (0)
; #define PG8_MMA(ai, bj, At, Bt) do { __builtin_amdgcn_s_setprio(1); _Pragma("unroll") for (int m = 0; m < 4; ++m) _Pragma("unroll") for (int n = 0; n < 2; ++n) _Pragma("unroll") for (int k = 0; k < 2; ++k) \
;         acc[ai][bj][m][n] = __builtin_amdgcn_mfma_f32_16x16x32_bf16(Bt[n][k], At[m][k], acc[ai][bj][m][n], 0, 0, 0); __builtin_amdgcn_s_setprio(0); } while (0)
; #define PG8_WAIT_V(n) asm volatile("s_waitcnt vmcnt(" #n ")" ::: "memory")
; #define PG8_WAIT_L(n) asm volatile("s_waitcnt lgkmcnt(" #n ")" ::: "memory")
; #define PG8_BAR __builtin_amdgcn_s_barrier()
; #define PG8_SCHED __builtin_amdgcn_sched_barrier(0)
; template <class Desc, class Epi, bool ALIGN_EPI>
; __device__ __forceinline__ void gemm_phase(LAS unsigned char* lds, const Desc& D, const Epi& E, int G, int c) {
;     ...
;             PG8_WAIT_V(8); PG8_WAIT_L(0); PG8_BAR; PG8_MMA(1, 0, At, B0); PG8_MMA(1, 1, At, B1); PG8_BAR; PG8_SCHED;
;             PG8_LDB(B0, 1, 0); PG8_LDB(B1, 1, 1); PG8_SCHED; PG8_LDA(At, 1, 0); PG8_STAGE(PG8_SA(0, 1), a2 + hstepA, voffA);
;             PG8_WAIT_V(8); PG8_WAIT_L(0); PG8_BAR; PG8_MMA(0, 0, At, B0); PG8_MMA(0, 1, At, B1); PG8_BAR; PG8_SCHED;
	v_mfma_f32_16x16x32_bf16 v[64:67], v[140:143], v[178:181], v[64:67]
	v_mfma_f32_16x16x32_bf16 v[64:67], v[144:147], v[182:185], v[64:67]
	v_mfma_f32_16x16x32_bf16 v[52:55], v[148:151], v[178:181], v[52:55]
	v_mfma_f32_16x16x32_bf16 v[52:55], v[152:155], v[182:185], v[52:55]
	v_mfma_f32_16x16x32_bf16 v[60:63], v[156:159], v[178:181], v[60:63]
	v_mfma_f32_16x16x32_bf16 v[60:63], v[166:169], v[182:185], v[60:63]
	v_mfma_f32_16x16x32_bf16 v[56:59], v[170:173], v[178:181], v[56:59]
	v_mfma_f32_16x16x32_bf16 v[56:59], v[174:177], v[182:185], v[56:59]
	v_mfma_f32_16x16x32_bf16 v[44:47], v[170:173], v[186:189], v[44:47]
	v_mfma_f32_16x16x32_bf16 v[44:47], v[174:177], v[190:193], v[44:47]
	v_mfma_f32_16x16x32_bf16 v[48:51], v[156:159], v[186:189], v[48:51]
	v_mfma_f32_16x16x32_bf16 v[48:51], v[166:169], v[190:193], v[48:51]
	v_mfma_f32_16x16x32_bf16 v[20:23], v[148:151], v[186:189], v[20:23]
	v_mfma_f32_16x16x32_bf16 v[20:23], v[152:155], v[190:193], v[20:23]
	v_mfma_f32_16x16x32_bf16 v[32:35], v[140:143], v[186:189], v[32:35]
	v_mfma_f32_16x16x32_bf16 v[32:35], v[144:147], v[190:193], v[32:35]
	v_mfma_f32_16x16x32_bf16 v[16:19], v[140:143], v[194:197], v[16:19]
	v_mfma_f32_16x16x32_bf16 v[16:19], v[144:147], v[198:201], v[16:19]
	v_mfma_f32_16x16x32_bf16 v[12:15], v[148:151], v[194:197], v[12:15]
	v_mfma_f32_16x16x32_bf16 v[12:15], v[152:155], v[198:201], v[12:15]
	v_mfma_f32_16x16x32_bf16 v[40:43], v[156:159], v[194:197], v[40:43]
	v_mfma_f32_16x16x32_bf16 v[40:43], v[166:169], v[198:201], v[40:43]
	v_mfma_f32_16x16x32_bf16 v[36:39], v[170:173], v[194:197], v[36:39]
	v_mfma_f32_16x16x32_bf16 v[36:39], v[174:177], v[198:201], v[36:39]
	v_mfma_f32_16x16x32_bf16 v[24:27], v[170:173], v[202:205], v[24:27]
	v_mfma_f32_16x16x32_bf16 v[24:27], v[174:177], v[206:209], v[24:27]
	v_mfma_f32_16x16x32_bf16 v[28:31], v[156:159], v[202:205], v[28:31]
	v_mfma_f32_16x16x32_bf16 v[28:31], v[166:169], v[206:209], v[28:31]
	v_mfma_f32_16x16x32_bf16 v[4:7], v[148:151], v[202:205], v[4:7]
	v_mfma_f32_16x16x32_bf16 v[4:7], v[152:155], v[206:209], v[4:7]
	v_mfma_f32_16x16x32_bf16 v[8:11], v[140:143], v[202:205], v[8:11]
	v_mfma_f32_16x16x32_bf16 v[8:11], v[144:147], v[206:209], v[8:11]
	s_barrier
	ds_read_b128 v[140:143], v163 offset:32768
	ds_read_b128 v[144:147], v163 offset:33792
	ds_read_b128 v[148:151], v163 offset:34816
	ds_read_b128 v[152:155], v163 offset:35840
	ds_read_b128 v[156:159], v163 offset:49152
	ds_read_b128 v[166:169], v163 offset:50176
	ds_read_b128 v[170:173], v163 offset:51200
	ds_read_b128 v[174:177], v163 offset:52224
	s_add_u32 s46, s46, 0x100000
	s_addc_u32 s47, s47, 0
	s_mov_b32 m0, s58
	ds_read_b128 v[178:181], v162 offset:32768
	ds_read_b128 v[182:185], v162 offset:33792
	ds_read_b128 v[186:189], v162 offset:34816
	ds_read_b128 v[190:193], v162 offset:35840
	ds_read_b128 v[194:197], v162 offset:36864
	ds_read_b128 v[198:201], v162 offset:37888
	ds_read_b128 v[202:205], v162 offset:38912
	ds_read_b128 v[206:209], v162 offset:39936
	global_load_lds_dwordx4 v132, s[46:47]
	s_mov_b32 m0, s59
	s_nop 0
	global_load_lds_dwordx4 v136, s[46:47]
	s_waitcnt vmcnt(8)
	s_waitcnt lgkmcnt(0)
	s_barrier
	v_mfma_f32_16x16x32_bf16 v[128:131], v[140:143], v[178:181], v[128:131]
	v_mfma_f32_16x16x32_bf16 v[128:131], v[144:147], v[182:185], v[128:131]
	v_mfma_f32_16x16x32_bf16 v[124:127], v[148:151], v[178:181], v[124:127]
	v_mfma_f32_16x16x32_bf16 v[124:127], v[152:155], v[182:185], v[124:127]
	v_mfma_f32_16x16x32_bf16 v[96:99], v[156:159], v[178:181], v[96:99]
	v_mfma_f32_16x16x32_bf16 v[96:99], v[166:169], v[182:185], v[96:99]
	v_mfma_f32_16x16x32_bf16 v[92:95], v[170:173], v[178:181], v[92:95]
	v_mfma_f32_16x16x32_bf16 v[92:95], v[174:177], v[182:185], v[92:95]
	v_mfma_f32_16x16x32_bf16 v[84:87], v[170:173], v[186:189], v[84:87]
	v_mfma_f32_16x16x32_bf16 v[84:87], v[174:177], v[190:193], v[84:87]
	v_mfma_f32_16x16x32_bf16 v[88:91], v[156:159], v[186:189], v[88:91]
	v_mfma_f32_16x16x32_bf16 v[88:91], v[166:169], v[190:193], v[88:91]
	v_mfma_f32_16x16x32_bf16 v[116:119], v[148:151], v[186:189], v[116:119]
	v_mfma_f32_16x16x32_bf16 v[116:119], v[152:155], v[190:193], v[116:119]
	v_mfma_f32_16x16x32_bf16 v[120:123], v[140:143], v[186:189], v[120:123]
	v_mfma_f32_16x16x32_bf16 v[120:123], v[144:147], v[190:193], v[120:123]
	v_mfma_f32_16x16x32_bf16 v[112:115], v[140:143], v[194:197], v[112:115]
	v_mfma_f32_16x16x32_bf16 v[112:115], v[144:147], v[198:201], v[112:115]
	v_mfma_f32_16x16x32_bf16 v[108:111], v[148:151], v[194:197], v[108:111]
	v_mfma_f32_16x16x32_bf16 v[108:111], v[152:155], v[198:201], v[108:111]
	v_mfma_f32_16x16x32_bf16 v[80:83], v[156:159], v[194:197], v[80:83]
	v_mfma_f32_16x16x32_bf16 v[80:83], v[166:169], v[198:201], v[80:83]
	v_mfma_f32_16x16x32_bf16 v[76:79], v[170:173], v[194:197], v[76:79]
	v_mfma_f32_16x16x32_bf16 v[76:79], v[174:177], v[198:201], v[76:79]
	v_mfma_f32_16x16x32_bf16 v[68:71], v[170:173], v[202:205], v[68:71]
	v_mfma_f32_16x16x32_bf16 v[68:71], v[174:177], v[206:209], v[68:71]
	v_mfma_f32_16x16x32_bf16 v[72:75], v[156:159], v[202:205], v[72:75]
	v_mfma_f32_16x16x32_bf16 v[72:75], v[166:169], v[206:209], v[72:75]
	v_mfma_f32_16x16x32_bf16 v[100:103], v[148:151], v[202:205], v[100:103]
	v_mfma_f32_16x16x32_bf16 v[100:103], v[152:155], v[206:209], v[100:103]
	v_mfma_f32_16x16x32_bf16 v[104:107], v[140:143], v[202:205], v[104:107]
	v_mfma_f32_16x16x32_bf16 v[104:107], v[144:147], v[206:209], v[104:107]
	s_barrier
; #define PG8_STAGE(bufoff, gbase, voff) do { _Pragma("unroll") for (int _i = 0; _i < 2; ++_i) \
;         __builtin_amdgcn_global_load_lds((const unsigned*)((const char*)(gbase) + (voff)[_i]), (LAS unsigned*)(lds + (bufoff) + ldsw + _i * 8192), 16, 0, 0); } while (0)
; #define PG8_LDA(dst, b, h) do { _Pragma("unroll") for (int m = 0; m < 4; ++m) _Pragma("unroll") for (int k = 0; k < 2; ++k) dst[m][k] = *(const LAS bf16x8*)(pA + PG8_SA(b, h) + m * 2048 + k * 1024); } while (0)
; #define PG8_MMA(ai, bj, At, Bt) do { __builtin_amdgcn_s_setprio(1); _Pragma("unroll") for (int m = 0; m < 4; ++m) _Pragma("unroll") for (int n = 0; n < 2; ++n) _Pragma("unroll") for (int k = 0; k < 2; ++k) \
;         acc[ai][bj][m][n] = __builtin_amdgcn_mfma_f32_16x16x32_bf16(Bt[n][k], At[m][k], acc[ai][bj][m][n], 0, 0, 0); __builtin_amdgcn_s_setprio(0); } while (0)
; #define PG8_WAIT_V(n) asm volatile("s_waitcnt vmcnt(" #n ")" ::: "memory")
; #define PG8_WAIT_L(n) asm volatile("s_waitcnt lgkmcnt(" #n ")" ::: "memory")
; #define PG8_BAR __builtin_amdgcn_s_barrier()
; #define PG8_SCHED __builtin_amdgcn_sched_barrier(0)
; template <class Desc, class Epi, bool ALIGN_EPI>
; __device__ __forceinline__ void gemm_phase(LAS unsigned char* lds, const Desc& D, const Epi& E, int G, int c) {
;     ...
;             PG8_LDA(At, 1, 1); PG8_STAGE(PG8_SB(1, 0), b3, voffB); PG8_STAGE(PG8_SB(1, 1), b3 + hstepB, voffB); PG8_STAGE(PG8_SA(1, 0), a3, voffA);
;             PG8_WAIT_V(8); PG8_WAIT_L(0); PG8_BAR; PG8_MMA(1, 0, At, B0); PG8_MMA(1, 1, At, B1); PG8_BAR; PG8_SCHED;
;         }
	s_mov_b32 m0, s61
	s_add_u32 s72, s34, 0x80
	s_addc_u32 s73, s35, 0
	s_add_u32 s34, s34, 0x100080
	s_addc_u32 s35, s35, 0
	ds_read_b128 v[178:181], v162 offset:49152
	ds_read_b128 v[182:185], v162 offset:50176
	ds_read_b128 v[186:189], v162 offset:51200
	ds_read_b128 v[190:193], v162 offset:52224
	ds_read_b128 v[194:197], v162 offset:53248
	ds_read_b128 v[198:201], v162 offset:54272
	ds_read_b128 v[202:205], v162 offset:55296
	ds_read_b128 v[206:209], v162 offset:56320
	global_load_lds_dwordx4 v134, s[72:73]
	s_mov_b32 m0, s62
	s_nop 0
	global_load_lds_dwordx4 v138, s[72:73]
	s_mov_b32 m0, s65
	s_nop 0
	global_load_lds_dwordx4 v134, s[34:35]
	s_mov_b32 m0, s67
	s_nop 0
	global_load_lds_dwordx4 v138, s[34:35]
	s_sub_u32 s74, s46, 0xfff80
	s_subb_u32 s75, s47, 0
	s_mov_b32 m0, s63
	s_nop 0
	global_load_lds_dwordx4 v132, s[74:75]
	s_mov_b32 m0, s64
	s_nop 0
	global_load_lds_dwordx4 v136, s[74:75]
	s_waitcnt vmcnt(8)
	s_waitcnt lgkmcnt(0)
	s_barrier
	v_mfma_f32_16x16x32_bf16 v[64:67], v[140:143], v[178:181], v[64:67]
	v_mfma_f32_16x16x32_bf16 v[64:67], v[144:147], v[182:185], v[64:67]
	v_mfma_f32_16x16x32_bf16 v[52:55], v[148:151], v[178:181], v[52:55]
	v_mfma_f32_16x16x32_bf16 v[52:55], v[152:155], v[182:185], v[52:55]
	v_mfma_f32_16x16x32_bf16 v[60:63], v[156:159], v[178:181], v[60:63]
	v_mfma_f32_16x16x32_bf16 v[60:63], v[166:169], v[182:185], v[60:63]
	v_mfma_f32_16x16x32_bf16 v[56:59], v[170:173], v[178:181], v[56:59]
	v_mfma_f32_16x16x32_bf16 v[56:59], v[174:177], v[182:185], v[56:59]
	v_mfma_f32_16x16x32_bf16 v[44:47], v[170:173], v[186:189], v[44:47]
	v_mfma_f32_16x16x32_bf16 v[44:47], v[174:177], v[190:193], v[44:47]
	v_mfma_f32_16x16x32_bf16 v[48:51], v[156:159], v[186:189], v[48:51]
	v_mfma_f32_16x16x32_bf16 v[48:51], v[166:169], v[190:193], v[48:51]
	v_mfma_f32_16x16x32_bf16 v[20:23], v[148:151], v[186:189], v[20:23]
	v_mfma_f32_16x16x32_bf16 v[20:23], v[152:155], v[190:193], v[20:23]
	v_mfma_f32_16x16x32_bf16 v[32:35], v[140:143], v[186:189], v[32:35]
	v_mfma_f32_16x16x32_bf16 v[32:35], v[144:147], v[190:193], v[32:35]
	v_mfma_f32_16x16x32_bf16 v[16:19], v[140:143], v[194:197], v[16:19]
	v_mfma_f32_16x16x32_bf16 v[16:19], v[144:147], v[198:201], v[16:19]
	v_mfma_f32_16x16x32_bf16 v[12:15], v[148:151], v[194:197], v[12:15]
	v_mfma_f32_16x16x32_bf16 v[12:15], v[152:155], v[198:201], v[12:15]
	v_mfma_f32_16x16x32_bf16 v[40:43], v[156:159], v[194:197], v[40:43]
	v_mfma_f32_16x16x32_bf16 v[40:43], v[166:169], v[198:201], v[40:43]
	v_mfma_f32_16x16x32_bf16 v[36:39], v[170:173], v[194:197], v[36:39]
	v_mfma_f32_16x16x32_bf16 v[36:39], v[174:177], v[198:201], v[36:39]
	v_mfma_f32_16x16x32_bf16 v[24:27], v[170:173], v[202:205], v[24:27]
	v_mfma_f32_16x16x32_bf16 v[24:27], v[174:177], v[206:209], v[24:27]
	v_mfma_f32_16x16x32_bf16 v[28:31], v[156:159], v[202:205], v[28:31]
	v_mfma_f32_16x16x32_bf16 v[28:31], v[166:169], v[206:209], v[28:31]
	v_mfma_f32_16x16x32_bf16 v[4:7], v[148:151], v[202:205], v[4:7]
	v_mfma_f32_16x16x32_bf16 v[4:7], v[152:155], v[206:209], v[4:7]
	v_mfma_f32_16x16x32_bf16 v[8:11], v[140:143], v[202:205], v[8:11]
	v_mfma_f32_16x16x32_bf16 v[8:11], v[144:147], v[206:209], v[8:11]
	s_barrier
	s_cmp_ge_u32 s30, s2
	s_cbranch_scc1 .LBB0_1591

;     __device__ __forceinline__ int nt(const Unit& u) const { return (u.pn >> 1) < 2 ? 22 : 20; }
; #define PG8_STAGE(bufoff, gbase, voff) do { _Pragma("unroll") for (int _i = 0; _i < 2; ++_i) \
;         __builtin_amdgcn_global_load_lds((const unsigned*)((const char*)(gbase) + (voff)[_i]), (LAS unsigned*)(lds + (bufoff) + ldsw + _i * 8192), 16, 0, 0); } while (0)
; #define PG8_LDA(dst, b, h) do { _Pragma("unroll") for (int m = 0; m < 4; ++m) _Pragma("unroll") for (int k = 0; k < 2; ++k) dst[m][k] = *(const LAS bf16x8*)(pA + PG8_SA(b, h) + m * 2048 + k * 1024); } while (0)
; #define PG8_LDB(dst, b, h) do { _Pragma("unroll") for (int n = 0; n < 2; ++n) _Pragma("unroll") for (int k = 0; k < 2; ++k) dst[n][k] = *(const LAS bf16x8*)(pB + (PG8_SB(b, h) - 4 * HTB) + n * 2048 + k * 1024); } while (0)
; #define PG8_MMA(ai, bj, At, Bt) do { __builtin_amdgcn_s_setprio(1); _Pragma("unroll") for (int m = 0; m < 4; ++m) _Pragma("unroll") for (int n = 0; n < 2; ++n) _Pragma("unroll") for (int k = 0; k < 2; ++k) \
;         acc[ai][bj][m][n] = __builtin_amdgcn_mfma_f32_16x16x32_bf16(Bt[n][k], At[m][k], acc[ai][bj][m][n], 0, 0, 0); __builtin_amdgcn_s_setprio(0); } while (0)
; #define PG8_WAIT_V(n) asm volatile("s_waitcnt vmcnt(" #n ")" ::: "memory")
; #define PG8_BAR __builtin_amdgcn_s_barrier()
; template <class Desc, class Epi, bool ALIGN_EPI>
; __device__ __forceinline__ void gemm_phase(LAS unsigned char* lds, const Desc& D, const Epi& E, int G, int c) {
;     ...
;         for (int t = 0; t < nt; t += 2) {
;             const bool last = (t == nt - 2);
;             if (last && has_next) PG8_AWAIT(nxt);
;             const char* a1 = cA + (size_t)(t + 1) * kstep;
;             const char* a2 = last ? nA : cA + (size_t)(t + 2) * kstep; const char* b2 = last ? nB : cB + (size_t)(t + 2) * kstep;
;             const char* a3 = a2 + kstep; const char* b3 = b2 + kstep;
;             PG8_LDB(B0, 0, 0); PG8_LDB(B1, 0, 1); PG8_SCHED; PG8_LDA(At, 0, 0); PG8_STAGE(PG8_SA(1, 1), a1 + hstepA, voffA);
;             PG8_WAIT_V(8); PG8_WAIT_L(0); PG8_BAR; PG8_MMA(0, 0, At, B0); PG8_MMA(0, 1, At, B1); PG8_BAR; PG8_SCHED;
;             PG8_LDA(At, 0, 1); PG8_STAGE(PG8_SB(0, 0), b2, voffB); PG8_STAGE(PG8_SB(0, 1), b2 + hstepB, voffB); PG8_STAGE(PG8_SA(0, 0), a2, voffA);
;             PG8_WAIT_V(8); PG8_WAIT_L(0); PG8_BAR; PG8_MMA(1, 0, At, B0); PG8_MMA(1, 1, At, B1); PG8_BAR; PG8_SCHED;
.LBB0_1765:
	s_or_b32 s14, s39, 1
	s_lshl_b64 s[40:41], s[14:15], 7
	s_add_i32 s14, s39, 2
	s_lshl_b64 s[42:43], s[14:15], 7
	s_add_u32 s39, s12, s42
	s_waitcnt lgkmcnt(0)
	ds_read_b128 v[132:135], v248
	ds_read_b128 v[136:139], v248 offset:1024
	ds_read_b128 v[140:143], v248 offset:2048
	ds_read_b128 v[144:147], v248 offset:3072
	ds_read_b128 v[148:151], v248 offset:16384
	ds_read_b128 v[152:155], v248 offset:17408
	ds_read_b128 v[156:159], v248 offset:18432
	ds_read_b128 v[160:163], v248 offset:19456
	s_addc_u32 s78, s13, s43
	s_and_b64 s[30:31], s[20:21], exec
	s_cselect_b32 s31, s49, s78
	s_cselect_b32 s30, s48, s39
	s_add_u32 s39, s16, s42
	s_addc_u32 s42, s17, s43
	s_and_b64 s[20:21], s[20:21], exec
	s_cselect_b32 s21, s51, s42
	s_cselect_b32 s20, s50, s39
	s_add_u32 s39, s12, s40
	s_addc_u32 s41, s13, s41
	s_add_u32 s40, s39, 0x2b0000
	s_addc_u32 s41, s41, 0
	s_add_i32 m0, s56, 0xc000
	ds_read_b128 v[164:167], v247
	ds_read_b128 v[168:171], v247 offset:1024
	ds_read_b128 v[172:175], v247 offset:2048
	ds_read_b128 v[176:179], v247 offset:3072
	ds_read_b128 v[180:183], v247 offset:4096
	ds_read_b128 v[184:187], v247 offset:5120
	ds_read_b128 v[188:191], v247 offset:6144
	ds_read_b128 v[192:195], v247 offset:7168
	global_load_lds_dwordx4 v200, s[40:41]
	s_add_i32 m0, s56, 0xe000
	s_nop 0
	global_load_lds_dwordx4 v204, s[40:41]
	s_waitcnt vmcnt(8)
	s_waitcnt lgkmcnt(0)
	s_barrier
	v_mfma_f32_16x16x32_bf16 v[128:131], v[132:135], v[164:167], v[128:131]
	v_mfma_f32_16x16x32_bf16 v[128:131], v[136:139], v[168:171], v[128:131]
	v_mfma_f32_16x16x32_bf16 v[124:127], v[140:143], v[164:167], v[124:127]
	v_mfma_f32_16x16x32_bf16 v[124:127], v[144:147], v[168:171], v[124:127]
	v_mfma_f32_16x16x32_bf16 v[96:99], v[148:151], v[164:167], v[96:99]
	v_mfma_f32_16x16x32_bf16 v[96:99], v[152:155], v[168:171], v[96:99]
	v_mfma_f32_16x16x32_bf16 v[92:95], v[156:159], v[164:167], v[92:95]
	v_mfma_f32_16x16x32_bf16 v[92:95], v[160:163], v[168:171], v[92:95]
	v_mfma_f32_16x16x32_bf16 v[80:83], v[156:159], v[172:175], v[80:83]
	v_mfma_f32_16x16x32_bf16 v[80:83], v[160:163], v[176:179], v[80:83]
	v_mfma_f32_16x16x32_bf16 v[88:91], v[148:151], v[172:175], v[88:91]
	v_mfma_f32_16x16x32_bf16 v[88:91], v[152:155], v[176:179], v[88:91]
	v_mfma_f32_16x16x32_bf16 v[116:119], v[140:143], v[172:175], v[116:119]
	v_mfma_f32_16x16x32_bf16 v[116:119], v[144:147], v[176:179], v[116:119]
	v_mfma_f32_16x16x32_bf16 v[120:123], v[132:135], v[172:175], v[120:123]
	v_mfma_f32_16x16x32_bf16 v[120:123], v[136:139], v[176:179], v[120:123]
	v_mfma_f32_16x16x32_bf16 v[112:115], v[132:135], v[180:183], v[112:115]
	v_mfma_f32_16x16x32_bf16 v[112:115], v[136:139], v[184:187], v[112:115]
	v_mfma_f32_16x16x32_bf16 v[108:111], v[140:143], v[180:183], v[108:111]
	v_mfma_f32_16x16x32_bf16 v[108:111], v[144:147], v[184:187], v[108:111]
	v_mfma_f32_16x16x32_bf16 v[64:67], v[148:151], v[180:183], v[64:67]
	v_mfma_f32_16x16x32_bf16 v[64:67], v[152:155], v[184:187], v[64:67]
	v_mfma_f32_16x16x32_bf16 v[52:55], v[156:159], v[180:183], v[52:55]
	v_mfma_f32_16x16x32_bf16 v[52:55], v[160:163], v[184:187], v[52:55]
	v_mfma_f32_16x16x32_bf16 v[20:23], v[156:159], v[188:191], v[20:23]
	v_mfma_f32_16x16x32_bf16 v[20:23], v[160:163], v[192:195], v[20:23]
	v_mfma_f32_16x16x32_bf16 v[32:35], v[148:151], v[188:191], v[32:35]
	v_mfma_f32_16x16x32_bf16 v[32:35], v[152:155], v[192:195], v[32:35]
	v_mfma_f32_16x16x32_bf16 v[100:103], v[140:143], v[188:191], v[100:103]
	v_mfma_f32_16x16x32_bf16 v[100:103], v[144:147], v[192:195], v[100:103]
	v_mfma_f32_16x16x32_bf16 v[104:107], v[132:135], v[188:191], v[104:107]
	v_mfma_f32_16x16x32_bf16 v[104:107], v[136:139], v[192:195], v[104:107]
	s_barrier
	s_mov_b32 m0, s57
	s_add_u32 s40, s20, 0x2b0000
	s_addc_u32 s41, s21, 0
	ds_read_b128 v[164:167], v247 offset:16384
	ds_read_b128 v[168:171], v247 offset:17408
	ds_read_b128 v[172:175], v247 offset:18432
	ds_read_b128 v[176:179], v247 offset:19456
	ds_read_b128 v[180:183], v247 offset:20480
	ds_read_b128 v[184:187], v247 offset:21504
	ds_read_b128 v[188:191], v247 offset:22528
	ds_read_b128 v[192:195], v247 offset:23552
	global_load_lds_dwordx4 v202, s[20:21]
	s_mov_b32 m0, s58
	s_nop 0
	global_load_lds_dwordx4 v206, s[20:21]
	s_mov_b32 m0, s59
	s_nop 0
	global_load_lds_dwordx4 v202, s[40:41]
	s_mov_b32 m0, s60
	s_nop 0
	global_load_lds_dwordx4 v206, s[40:41]
	s_mov_b32 m0, s56
	s_nop 0
	global_load_lds_dwordx4 v200, s[30:31]
	s_mov_b32 m0, s61
	s_nop 0
	global_load_lds_dwordx4 v204, s[30:31]
	s_waitcnt vmcnt(8)
	s_waitcnt lgkmcnt(0)
	s_barrier
; #define PG8_STAGE(bufoff, gbase, voff) do { _Pragma("unroll") for (int _i = 0; _i < 2; ++_i) \
;         __builtin_amdgcn_global_load_lds((const unsigned*)((const char*)(gbase) + (voff)[_i]), (LAS unsigned*)(lds + (bufoff) + ldsw + _i * 8192), 16, 0, 0); } while (0)
; #define PG8_LDA(dst, b, h) do { _Pragma("unroll") for (int m = 0; m < 4; ++m) _Pragma("unroll") for (int k = 0; k < 2; ++k) dst[m][k] = *(const LAS bf16x8*)(pA + PG8_SA(b, h) + m * 2048 + k * 1024); } while (0)
; #define PG8_LDB(dst, b, h) do { _Pragma("unroll") for (int n = 0; n < 2; ++n) _Pragma("unroll") for (int k = 0; k < 2; ++k) dst[n][k] = *(const LAS bf16x8*)(pB + (PG8_SB(b, h) - 4 * HTB) + n * 2048 + k * 1024); } while (0)
; #define PG8_MMA(ai, bj, At, Bt) do { __builtin_amdgcn_s_setprio(1); _Pragma("unroll") for (int m = 0; m < 4; ++m) _Pragma("unroll") for (int n = 0; n < 2; ++n) _Pragma("unroll") for (int k = 0; k < 2; ++k) \
;         acc[ai][bj][m][n] = __builtin_amdgcn_mfma_f32_16x16x32_bf16(Bt[n][k], At[m][k], acc[ai][bj][m][n], 0, 0, 0); __builtin_amdgcn_s_setprio(0); } while (0)
; #define PG8_WAIT_V(n) asm volatile("s_waitcnt vmcnt(" #n ")" ::: "memory")
; #define PG8_WAIT_L(n) asm volatile("s_waitcnt lgkmcnt(" #n ")" ::: "memory")
; #define PG8_BAR __builtin_amdgcn_s_barrier()
; #define PG8_SCHED __builtin_amdgcn_sched_barrier(0)
; template <class Desc, class Epi, bool ALIGN_EPI>
; __device__ __forceinline__ void gemm_phase(LAS unsigned char* lds, const Desc& D, const Epi& E, int G, int c) {
;     ...
;             PG8_WAIT_V(8); PG8_WAIT_L(0); PG8_BAR; PG8_MMA(1, 0, At, B0); PG8_MMA(1, 1, At, B1); PG8_BAR; PG8_SCHED;
;             PG8_LDB(B0, 1, 0); PG8_LDB(B1, 1, 1); PG8_SCHED; PG8_LDA(At, 1, 0); PG8_STAGE(PG8_SA(0, 1), a2 + hstepA, voffA);
;             PG8_WAIT_V(8); PG8_WAIT_L(0); PG8_BAR; PG8_MMA(0, 0, At, B0); PG8_MMA(0, 1, At, B1); PG8_BAR; PG8_SCHED;
	v_mfma_f32_16x16x32_bf16 v[84:87], v[132:135], v[164:167], v[84:87]
	v_mfma_f32_16x16x32_bf16 v[84:87], v[136:139], v[168:171], v[84:87]
	v_mfma_f32_16x16x32_bf16 v[76:79], v[140:143], v[164:167], v[76:79]
	v_mfma_f32_16x16x32_bf16 v[76:79], v[144:147], v[168:171], v[76:79]
	v_mfma_f32_16x16x32_bf16 v[40:43], v[148:151], v[164:167], v[40:43]
	v_mfma_f32_16x16x32_bf16 v[40:43], v[152:155], v[168:171], v[40:43]
	v_mfma_f32_16x16x32_bf16 v[36:39], v[156:159], v[164:167], v[36:39]
	v_mfma_f32_16x16x32_bf16 v[36:39], v[160:163], v[168:171], v[36:39]
	v_mfma_f32_16x16x32_bf16 v[24:27], v[156:159], v[172:175], v[24:27]
	v_mfma_f32_16x16x32_bf16 v[24:27], v[160:163], v[176:179], v[24:27]
	v_mfma_f32_16x16x32_bf16 v[28:31], v[148:151], v[172:175], v[28:31]
	v_mfma_f32_16x16x32_bf16 v[28:31], v[152:155], v[176:179], v[28:31]
	v_mfma_f32_16x16x32_bf16 v[68:71], v[140:143], v[172:175], v[68:71]
	v_mfma_f32_16x16x32_bf16 v[68:71], v[144:147], v[176:179], v[68:71]
	v_mfma_f32_16x16x32_bf16 v[72:75], v[132:135], v[172:175], v[72:75]
	v_mfma_f32_16x16x32_bf16 v[72:75], v[136:139], v[176:179], v[72:75]
	v_mfma_f32_16x16x32_bf16 v[60:63], v[132:135], v[180:183], v[60:63]
	v_mfma_f32_16x16x32_bf16 v[60:63], v[136:139], v[184:187], v[60:63]
	v_mfma_f32_16x16x32_bf16 v[56:59], v[140:143], v[180:183], v[56:59]
	v_mfma_f32_16x16x32_bf16 v[56:59], v[144:147], v[184:187], v[56:59]
	v_mfma_f32_16x16x32_bf16 v[16:19], v[148:151], v[180:183], v[16:19]
	v_mfma_f32_16x16x32_bf16 v[16:19], v[152:155], v[184:187], v[16:19]
	v_mfma_f32_16x16x32_bf16 v[12:15], v[156:159], v[180:183], v[12:15]
	v_mfma_f32_16x16x32_bf16 v[12:15], v[160:163], v[184:187], v[12:15]
	v_mfma_f32_16x16x32_bf16 v[4:7], v[156:159], v[188:191], v[4:7]
	v_mfma_f32_16x16x32_bf16 v[4:7], v[160:163], v[192:195], v[4:7]
	v_mfma_f32_16x16x32_bf16 v[8:11], v[148:151], v[188:191], v[8:11]
	v_mfma_f32_16x16x32_bf16 v[8:11], v[152:155], v[192:195], v[8:11]
	v_mfma_f32_16x16x32_bf16 v[44:47], v[140:143], v[188:191], v[44:47]
	v_mfma_f32_16x16x32_bf16 v[44:47], v[144:147], v[192:195], v[44:47]
	v_mfma_f32_16x16x32_bf16 v[48:51], v[132:135], v[188:191], v[48:51]
	v_mfma_f32_16x16x32_bf16 v[48:51], v[136:139], v[192:195], v[48:51]
	s_barrier
	ds_read_b128 v[132:135], v248 offset:32768
	ds_read_b128 v[136:139], v248 offset:33792
	ds_read_b128 v[140:143], v248 offset:34816
	ds_read_b128 v[144:147], v248 offset:35840
	ds_read_b128 v[148:151], v248 offset:49152
	ds_read_b128 v[152:155], v248 offset:50176
	ds_read_b128 v[156:159], v248 offset:51200
	ds_read_b128 v[160:163], v248 offset:52224
	s_add_u32 s30, s30, 0x2b0000
	s_addc_u32 s31, s31, 0
	s_mov_b32 m0, s62
	ds_read_b128 v[164:167], v247 offset:32768
	ds_read_b128 v[168:171], v247 offset:33792
	ds_read_b128 v[172:175], v247 offset:34816
	ds_read_b128 v[176:179], v247 offset:35840
	ds_read_b128 v[180:183], v247 offset:36864
	ds_read_b128 v[184:187], v247 offset:37888
	ds_read_b128 v[188:191], v247 offset:38912
	ds_read_b128 v[192:195], v247 offset:39936
	global_load_lds_dwordx4 v200, s[30:31]
	s_mov_b32 m0, s63
	s_nop 0
	global_load_lds_dwordx4 v204, s[30:31]
	s_waitcnt vmcnt(8)
	s_waitcnt lgkmcnt(0)
	s_barrier
	v_mfma_f32_16x16x32_bf16 v[128:131], v[132:135], v[164:167], v[128:131]
	v_mfma_f32_16x16x32_bf16 v[128:131], v[136:139], v[168:171], v[128:131]
	v_mfma_f32_16x16x32_bf16 v[124:127], v[140:143], v[164:167], v[124:127]
	v_mfma_f32_16x16x32_bf16 v[124:127], v[144:147], v[168:171], v[124:127]
	v_mfma_f32_16x16x32_bf16 v[96:99], v[148:151], v[164:167], v[96:99]
	v_mfma_f32_16x16x32_bf16 v[96:99], v[152:155], v[168:171], v[96:99]
	v_mfma_f32_16x16x32_bf16 v[92:95], v[156:159], v[164:167], v[92:95]
	v_mfma_f32_16x16x32_bf16 v[92:95], v[160:163], v[168:171], v[92:95]
	v_mfma_f32_16x16x32_bf16 v[80:83], v[156:159], v[172:175], v[80:83]
	v_mfma_f32_16x16x32_bf16 v[80:83], v[160:163], v[176:179], v[80:83]
	v_mfma_f32_16x16x32_bf16 v[88:91], v[148:151], v[172:175], v[88:91]
	v_mfma_f32_16x16x32_bf16 v[88:91], v[152:155], v[176:179], v[88:91]
	v_mfma_f32_16x16x32_bf16 v[116:119], v[140:143], v[172:175], v[116:119]
	v_mfma_f32_16x16x32_bf16 v[116:119], v[144:147], v[176:179], v[116:119]
	v_mfma_f32_16x16x32_bf16 v[120:123], v[132:135], v[172:175], v[120:123]
	v_mfma_f32_16x16x32_bf16 v[120:123], v[136:139], v[176:179], v[120:123]
	v_mfma_f32_16x16x32_bf16 v[112:115], v[132:135], v[180:183], v[112:115]
	v_mfma_f32_16x16x32_bf16 v[112:115], v[136:139], v[184:187], v[112:115]
	v_mfma_f32_16x16x32_bf16 v[108:111], v[140:143], v[180:183], v[108:111]
	v_mfma_f32_16x16x32_bf16 v[108:111], v[144:147], v[184:187], v[108:111]
	v_mfma_f32_16x16x32_bf16 v[64:67], v[148:151], v[180:183], v[64:67]
	v_mfma_f32_16x16x32_bf16 v[64:67], v[152:155], v[184:187], v[64:67]
	v_mfma_f32_16x16x32_bf16 v[52:55], v[156:159], v[180:183], v[52:55]
	v_mfma_f32_16x16x32_bf16 v[52:55], v[160:163], v[184:187], v[52:55]
	v_mfma_f32_16x16x32_bf16 v[20:23], v[156:159], v[188:191], v[20:23]
	v_mfma_f32_16x16x32_bf16 v[20:23], v[160:163], v[192:195], v[20:23]
	v_mfma_f32_16x16x32_bf16 v[32:35], v[148:151], v[188:191], v[32:35]
	v_mfma_f32_16x16x32_bf16 v[32:35], v[152:155], v[192:195], v[32:35]
	v_mfma_f32_16x16x32_bf16 v[100:103], v[140:143], v[188:191], v[100:103]
	v_mfma_f32_16x16x32_bf16 v[100:103], v[144:147], v[192:195], v[100:103]
	v_mfma_f32_16x16x32_bf16 v[104:107], v[132:135], v[188:191], v[104:107]
	v_mfma_f32_16x16x32_bf16 v[104:107], v[136:139], v[192:195], v[104:107]
	s_barrier
; #define PG8_STAGE(bufoff, gbase, voff) do { _Pragma("unroll") for (int _i = 0; _i < 2; ++_i) \
;         __builtin_amdgcn_global_load_lds((const unsigned*)((const char*)(gbase) + (voff)[_i]), (LAS unsigned*)(lds + (bufoff) + ldsw + _i * 8192), 16, 0, 0); } while (0)
; #define PG8_LDA(dst, b, h) do { _Pragma("unroll") for (int m = 0; m < 4; ++m) _Pragma("unroll") for (int k = 0; k < 2; ++k) dst[m][k] = *(const LAS bf16x8*)(pA + PG8_SA(b, h) + m * 2048 + k * 1024); } while (0)
; #define PG8_MMA(ai, bj, At, Bt) do { __builtin_amdgcn_s_setprio(1); _Pragma("unroll") for (int m = 0; m < 4; ++m) _Pragma("unroll") for (int n = 0; n < 2; ++n) _Pragma("unroll") for (int k = 0; k < 2; ++k) \
;         acc[ai][bj][m][n] = __builtin_amdgcn_mfma_f32_16x16x32_bf16(Bt[n][k], At[m][k], acc[ai][bj][m][n], 0, 0, 0); __builtin_amdgcn_s_setprio(0); } while (0)
; #define PG8_WAIT_V(n) asm volatile("s_waitcnt vmcnt(" #n ")" ::: "memory")
; #define PG8_WAIT_L(n) asm volatile("s_waitcnt lgkmcnt(" #n ")" ::: "memory")
; #define PG8_BAR __builtin_amdgcn_s_barrier()
; #define PG8_SCHED __builtin_amdgcn_sched_barrier(0)
; template <class Desc, class Epi, bool ALIGN_EPI>
; __device__ __forceinline__ void gemm_phase(LAS unsigned char* lds, const Desc& D, const Epi& E, int G, int c) {
;     ...
;             PG8_LDA(At, 1, 1); PG8_STAGE(PG8_SB(1, 0), b3, voffB); PG8_STAGE(PG8_SB(1, 1), b3 + hstepB, voffB); PG8_STAGE(PG8_SA(1, 0), a3, voffA);
;             PG8_WAIT_V(8); PG8_WAIT_L(0); PG8_BAR; PG8_MMA(1, 0, At, B0); PG8_MMA(1, 1, At, B1); PG8_BAR; PG8_SCHED;
;         }
	s_mov_b32 m0, s64
	s_add_u32 s40, s20, 0x80
	s_addc_u32 s41, s21, 0
	s_add_u32 s20, s20, 0x2b0080
	s_addc_u32 s21, s21, 0
	ds_read_b128 v[164:167], v247 offset:49152
	ds_read_b128 v[168:171], v247 offset:50176
	ds_read_b128 v[172:175], v247 offset:51200
	ds_read_b128 v[176:179], v247 offset:52224
	ds_read_b128 v[180:183], v247 offset:53248
	ds_read_b128 v[184:187], v247 offset:54272
	ds_read_b128 v[188:191], v247 offset:55296
	ds_read_b128 v[192:195], v247 offset:56320
	global_load_lds_dwordx4 v202, s[40:41]
	s_mov_b32 m0, s65
	s_nop 0
	global_load_lds_dwordx4 v206, s[40:41]
	s_mov_b32 m0, s69
	s_nop 0
	global_load_lds_dwordx4 v202, s[20:21]
	s_mov_b32 m0, s70
	s_nop 0
	global_load_lds_dwordx4 v206, s[20:21]
	s_sub_u32 s42, s30, 0x2aff80
	s_subb_u32 s43, s31, 0
	s_mov_b32 m0, s66
	s_nop 0
	global_load_lds_dwordx4 v200, s[42:43]
	s_mov_b32 m0, s67
	s_nop 0
	global_load_lds_dwordx4 v204, s[42:43]
	s_waitcnt vmcnt(8)
	s_waitcnt lgkmcnt(0)
	s_barrier
	v_mfma_f32_16x16x32_bf16 v[84:87], v[132:135], v[164:167], v[84:87]
	v_mfma_f32_16x16x32_bf16 v[84:87], v[136:139], v[168:171], v[84:87]
	v_mfma_f32_16x16x32_bf16 v[76:79], v[140:143], v[164:167], v[76:79]
	v_mfma_f32_16x16x32_bf16 v[76:79], v[144:147], v[168:171], v[76:79]
	v_mfma_f32_16x16x32_bf16 v[40:43], v[148:151], v[164:167], v[40:43]
	v_mfma_f32_16x16x32_bf16 v[40:43], v[152:155], v[168:171], v[40:43]
	v_mfma_f32_16x16x32_bf16 v[36:39], v[156:159], v[164:167], v[36:39]
	v_mfma_f32_16x16x32_bf16 v[36:39], v[160:163], v[168:171], v[36:39]
	v_mfma_f32_16x16x32_bf16 v[24:27], v[156:159], v[172:175], v[24:27]
	v_mfma_f32_16x16x32_bf16 v[24:27], v[160:163], v[176:179], v[24:27]
	v_mfma_f32_16x16x32_bf16 v[28:31], v[148:151], v[172:175], v[28:31]
	v_mfma_f32_16x16x32_bf16 v[28:31], v[152:155], v[176:179], v[28:31]
	v_mfma_f32_16x16x32_bf16 v[68:71], v[140:143], v[172:175], v[68:71]
	v_mfma_f32_16x16x32_bf16 v[68:71], v[144:147], v[176:179], v[68:71]
	v_mfma_f32_16x16x32_bf16 v[72:75], v[132:135], v[172:175], v[72:75]
	v_mfma_f32_16x16x32_bf16 v[72:75], v[136:139], v[176:179], v[72:75]
	v_mfma_f32_16x16x32_bf16 v[60:63], v[132:135], v[180:183], v[60:63]
	v_mfma_f32_16x16x32_bf16 v[60:63], v[136:139], v[184:187], v[60:63]
	v_mfma_f32_16x16x32_bf16 v[56:59], v[140:143], v[180:183], v[56:59]
	v_mfma_f32_16x16x32_bf16 v[56:59], v[144:147], v[184:187], v[56:59]
	v_mfma_f32_16x16x32_bf16 v[16:19], v[148:151], v[180:183], v[16:19]
	v_mfma_f32_16x16x32_bf16 v[16:19], v[152:155], v[184:187], v[16:19]
	v_mfma_f32_16x16x32_bf16 v[12:15], v[156:159], v[180:183], v[12:15]
	v_mfma_f32_16x16x32_bf16 v[12:15], v[160:163], v[184:187], v[12:15]
	v_mfma_f32_16x16x32_bf16 v[4:7], v[156:159], v[188:191], v[4:7]
	v_mfma_f32_16x16x32_bf16 v[4:7], v[160:163], v[192:195], v[4:7]
	v_mfma_f32_16x16x32_bf16 v[8:11], v[148:151], v[188:191], v[8:11]
	v_mfma_f32_16x16x32_bf16 v[8:11], v[152:155], v[192:195], v[8:11]
	v_mfma_f32_16x16x32_bf16 v[44:47], v[140:143], v[188:191], v[44:47]
	v_mfma_f32_16x16x32_bf16 v[44:47], v[144:147], v[192:195], v[44:47]
	v_mfma_f32_16x16x32_bf16 v[48:51], v[132:135], v[188:191], v[48:51]
	v_mfma_f32_16x16x32_bf16 v[48:51], v[136:139], v[192:195], v[48:51]
	s_barrier
	s_cmp_ge_u32 s14, s24
	s_mov_b32 s39, s14
	s_cbranch_scc1 .LBB0_1776
